# P1 schedule: M-tile group size 6 instead of 3 (same XCD remap) to halve weight-tile refetch
# speedup vs baseline: 1.0042x; 1.0032x over previous
;     __host__ __device__ bool next(int i, Unit& u) const {
;         const long L = (long)i * G + c; if (L >= nwg) return false;
;         int wgid = (int)L; { const int q = nwg / NXCD, r = nwg % NXCD, xcd = wgid % NXCD, off = wgid / NXCD; wgid = (xcd < r ? xcd * (q + 1) : r * (q + 1) + (xcd - r) * q) + off; }
;         const int nig = WGM * nN, gid = wgid / nig, fm = gid * WGM, gsz = (nM - fm) < WGM ? (nM - fm) : WGM;
;         u.pm = fm + ((wgid % nig) % gsz); u.pn = (wgid % nig) / gsz; return true;
; template <class Epi, class Sched, bool ALIGN_EPI = true>
; __device__ __forceinline__ void gemm_phase(LAS unsigned char* lds, const Gemm g, const Sched& S, const Epi& E) {
;     ...
;     if (!S.next(0, cur)) return;
.LBB0_113:
	s_or_b64 exec, exec, s[0:1]
	v_mov_b32_e32 v4, v181
	s_cmpk_lt_i32 s88, 0xbc5
	s_waitcnt lgkmcnt(0)
	s_barrier
	s_cselect_b64 s[0:1], -1, 0
	s_cmpk_gt_i32 s88, 0xbc4
	v_readfirstlane_b32 s4, v4
	s_cbranch_scc1 .LBB0_119
	s_and_b32 s5, s88, 7
	s_lshr_b32 s6, s88, 3
	s_mul_i32 s3, s5, 0x178
	s_min_u32 s5, s5, 5
	s_add_i32 s3, s3, s5
	s_add_i32 s3, s3, s6
	s_mul_hi_u32 s5, s3, 0x1dae608
	s_mul_i32 s6, s5, 0x8a
	s_sub_i32 s3, s3, s6
	s_mul_i32 s22, s5, 6
	s_cmp_eq_u32 s5, 21
	s_cbranch_scc1 .Lwgm5_a
	s_mul_hi_u32 s2, s3, 0x2aaaaaab
	s_mul_i32 s6, s2, 6
	s_branch .Lwgmj_a
.Lwgm5_a:
	s_mul_hi_u32 s2, s3, 0x33333334
	s_mul_i32 s6, s2, 5
.Lwgmj_a:
	s_sub_i32 s3, s3, s6
	s_add_i32 s22, s22, s3

;     __host__ __device__ bool next(int i, Unit& u) const {
;         const long L = (long)i * G + c; if (L >= nwg) return false;
;         int wgid = (int)L; { const int q = nwg / NXCD, r = nwg % NXCD, xcd = wgid % NXCD, off = wgid / NXCD; wgid = (xcd < r ? xcd * (q + 1) : r * (q + 1) + (xcd - r) * q) + off; }
;         const int nig = WGM * nN, gid = wgid / nig, fm = gid * WGM, gsz = (nM - fm) < WGM ? (nM - fm) : WGM;
;         u.pm = fm + ((wgid % nig) % gsz); u.pn = (wgid % nig) / gsz; return true;
; template <class Epi, class Sched, bool ALIGN_EPI = true>
; __device__ __forceinline__ void gemm_phase(LAS unsigned char* lds, const Gemm g, const Sched& S, const Epi& E) {
;     ...
;         const bool has_next = S.next(ui + 1, nxt);
.LBB0_125:
	s_add_i32 s29, s29, 1
	s_mul_i32 s0, s29, s45
	s_mul_hi_u32 s1, s29, s46
	s_add_i32 s1, s1, s0
	s_mul_i32 s0, s29, s46
	s_add_u32 s0, s0, s88
	s_addc_u32 s1, s1, s47
	v_cmp_gt_i64_e32 vcc, s[0:1], v[144:145]
	v_cmp_lt_i64_e64 s[4:5], s[0:1], v[142:143]
	s_cbranch_vccnz .LBB0_131
	s_and_b32 s1, s0, 7
	s_lshr_b32 s3, s0, 3
	s_mul_i32 s17, s1, 0x178
	s_min_u32 s1, s1, 5
	s_add_i32 s17, s17, s1
	s_add_i32 s17, s17, s3
	s_mul_hi_u32 s1, s17, 0x1dae608
	s_mul_i32 s3, s1, 0x8a
	s_sub_i32 s17, s17, s3
	s_mul_i32 s57, s1, 6
	s_cmp_eq_u32 s1, 21
	s_cbranch_scc1 .Lwgm5_b
	s_mul_hi_u32 s16, s17, 0x2aaaaaab
	s_mul_i32 s3, s16, 6
	s_branch .Lwgmj_b
.Lwgm5_b:
	s_mul_hi_u32 s16, s17, 0x33333334
	s_mul_i32 s3, s16, 5
.Lwgmj_b:
	s_sub_i32 s17, s17, s3
	s_add_i32 s57, s57, s17
